# PRE: team 0 sleeps 1024 cycles at the head of stage S4 (stagger probe)
# baseline (speedup 1.0000x reference)
.LBB0_83:
	s_or_b64 exec, exec, s[30:31]
	v_mov_b32_e32 v1, v180
	s_waitcnt lgkmcnt(0)
	s_barrier
	v_readlane_b32 s27, v253, 61
	v_and_b32_e32 v2, 31, v1
	v_or_b32_e32 v156, s43, v2
	v_bitop3_b32 v2, v2, 63, s43 bitop3:0x36
	v_ashrrev_i32_e32 v1, 5, v1
	v_cndmask_b32_e64 v2, v2, v156, s[36:37]
	v_mul_u32_u24_e32 v2, 0x90, v2
	s_waitcnt lgkmcnt(0)
	v_lshlrev_b32_e32 v3, 4, v1
	v_readlane_b32 s30, v253, 62
	v_add3_u32 v32, s27, v2, v3
	ds_read_b128 v[28:31], v32
	ds_read_b128 v[84:87], v32 offset:32
	ds_read_b128 v[88:91], v32 offset:64
	ds_read_b128 v[92:95], v32 offset:96
	v_add3_u32 v2, s30, v2, v3
	ds_read_b128 v[32:35], v2
	ds_read_b128 v[96:99], v2 offset:32
	ds_read_b128 v[148:151], v2 offset:64
	ds_read_b128 v[152:155], v2 offset:96
	s_waitcnt vmcnt(7) lgkmcnt(7)
	v_mfma_f32_32x32x16_bf16 v[36:51], v[20:23], v[28:31], 0
	v_add_u32_e32 v2, s47, v3
	v_add_u32_e32 v3, s46, v3
	v_lshlrev_b32_e32 v1, 3, v1
	s_waitcnt vmcnt(6) lgkmcnt(3)
	v_mfma_f32_32x32x16_bf16 v[20:35], v[24:27], v[32:35], 0
	s_waitcnt vmcnt(5)
	v_mfma_f32_32x32x16_bf16 v[36:51], v[60:63], v[84:87], v[36:51]
	ds_read_b128 v[60:63], v2 offset:32
	s_waitcnt vmcnt(4) lgkmcnt(3)
	v_mfma_f32_32x32x16_bf16 v[20:35], v[56:59], v[96:99], v[20:35]
	ds_read_b128 v[56:59], v2
	v_mov_b32_e32 v98, s30
	v_mov_b32_e32 v99, s27
	s_waitcnt vmcnt(3)
	v_mfma_f32_32x32x16_bf16 v[36:51], v[72:75], v[88:91], v[36:51]
	v_mov_b32_e32 v90, s76
	v_mad_u32_u24 v90, v156, s64, v90
	v_add3_u32 v1, v90, v1, s28
	s_waitcnt vmcnt(2) lgkmcnt(3)
	v_mfma_f32_32x32x16_bf16 v[20:35], v[64:67], v[148:151], v[20:35]
	s_waitcnt vmcnt(1)
	v_mfma_f32_32x32x16_bf16 v[36:51], v[68:71], v[92:95], v[36:51]
	ds_read_b128 v[64:67], v3
	ds_read_b128 v[68:71], v3 offset:32
	s_waitcnt vmcnt(0) lgkmcnt(4)
	v_mfma_f32_32x32x16_bf16 v[20:35], v[52:55], v[152:155], v[20:35]
	s_waitcnt lgkmcnt(2)
	s_nop 6
	v_add_f32_e32 v36, v36, v56
	v_mul_f32_e32 v36, 0xbfb8aa3b, v36
	v_exp_f32_e32 v36, v36
	s_nop 0
	v_add_f32_e32 v36, 1.0, v36
	s_waitcnt lgkmcnt(1)
	v_add_f32_e32 v20, v20, v64
	v_mul_f32_e32 v20, 0xbfb8aa3b, v20
	v_rcp_f32_e32 v74, v36
	v_add_f32_e32 v36, v37, v57
	v_exp_f32_e32 v20, v20
	v_mul_f32_e32 v36, 0xbfb8aa3b, v36
	v_add_f32_e32 v21, v21, v65
	v_exp_f32_e32 v36, v36
	v_mul_f32_e32 v21, 0xbfb8aa3b, v21
	v_exp_f32_e32 v21, v21
	v_add_f32_e32 v20, 1.0, v20
	v_rcp_f32_e32 v52, v20
	v_add_f32_e32 v20, 1.0, v36
	v_rcp_f32_e32 v75, v20
	v_add_f32_e32 v20, 1.0, v21
	v_add_f32_e32 v21, v38, v58
	v_mul_f32_e32 v21, 0xbfb8aa3b, v21
	v_add_f32_e32 v22, v22, v66
	v_exp_f32_e32 v21, v21
	v_mul_f32_e32 v22, 0xbfb8aa3b, v22
	v_exp_f32_e32 v22, v22
	v_rcp_f32_e32 v53, v20
	v_add_f32_e32 v20, 1.0, v21
	v_add_f32_e32 v21, v39, v59
	v_rcp_f32_e32 v84, v20
	v_add_f32_e32 v20, 1.0, v22
	v_mul_f32_e32 v21, 0xbfb8aa3b, v21
	v_add_f32_e32 v22, v23, v67
	v_exp_f32_e32 v21, v21
	v_mul_f32_e32 v22, 0xbfb8aa3b, v22
	v_exp_f32_e32 v22, v22
	v_rcp_f32_e32 v54, v20
	v_add_f32_e32 v20, 1.0, v21
	v_add_f32_e32 v21, v40, v60
	v_rcp_f32_e32 v85, v20
	v_add_f32_e32 v20, 1.0, v22
	v_mul_f32_e32 v21, 0xbfb8aa3b, v21
	s_waitcnt lgkmcnt(0)
	v_add_f32_e32 v22, v24, v68
	v_exp_f32_e32 v21, v21
	v_mul_f32_e32 v22, 0xbfb8aa3b, v22
	v_exp_f32_e32 v22, v22
	v_rcp_f32_e32 v55, v20
	v_add_f32_e32 v20, 1.0, v21
	v_add_f32_e32 v21, v41, v61
	v_rcp_f32_e32 v60, v20
	v_add_f32_e32 v20, 1.0, v22
	v_mul_f32_e32 v21, 0xbfb8aa3b, v21
	v_add_f32_e32 v22, v25, v69
	v_exp_f32_e32 v21, v21
	v_mul_f32_e32 v22, 0xbfb8aa3b, v22
	v_exp_f32_e32 v22, v22
	v_rcp_f32_e32 v56, v20
	v_add_f32_e32 v20, 1.0, v21
	v_add_f32_e32 v21, v42, v62
	v_rcp_f32_e32 v61, v20
	v_add_f32_e32 v20, 1.0, v22
	v_mul_f32_e32 v21, 0xbfb8aa3b, v21
	v_add_f32_e32 v22, v26, v70
	v_exp_f32_e32 v21, v21
	v_mul_f32_e32 v22, 0xbfb8aa3b, v22
	v_exp_f32_e32 v22, v22
	v_rcp_f32_e32 v57, v20
	v_add_f32_e32 v20, 1.0, v21
	v_rcp_f32_e32 v62, v20
	v_add_f32_e32 v20, 1.0, v22
	v_rcp_f32_e32 v58, v20
	v_add_f32_e32 v20, v43, v63
	v_mul_f32_e32 v20, 0xbfb8aa3b, v20
	v_exp_f32_e32 v20, v20
	v_add_f32_e32 v21, v27, v71
	v_mul_f32_e32 v21, 0xbfb8aa3b, v21
	v_exp_f32_e32 v24, v21
	v_add_f32_e32 v25, 1.0, v20
	ds_read_b128 v[20:23], v2 offset:64
	v_rcp_f32_e32 v63, v25
	v_add_f32_e32 v59, 1.0, v24
	ds_read_b128 v[24:27], v3 offset:64
	ds_read_b128 v[36:39], v2 offset:96
	ds_read_b128 v[40:43], v3 offset:96
	s_waitcnt lgkmcnt(3)
	v_add_f32_e32 v2, v44, v20
	v_mul_f32_e32 v2, 0xbfb8aa3b, v2
	s_waitcnt lgkmcnt(2)
	v_add_f32_e32 v3, v28, v24
	v_exp_f32_e32 v2, v2
	v_mul_f32_e32 v3, 0xbfb8aa3b, v3
	v_exp_f32_e32 v3, v3
	s_waitcnt lgkmcnt(1)
	v_add_f32_e32 v28, v51, v39
	v_add_f32_e32 v2, 1.0, v2
	v_rcp_f32_e32 v20, v2
	v_add_f32_e32 v2, 1.0, v3
	v_add_f32_e32 v3, v45, v21
	v_mul_f32_e32 v3, 0xbfb8aa3b, v3
	v_exp_f32_e32 v3, v3
	v_add_f32_e32 v21, v29, v25
	v_mul_f32_e32 v21, 0xbfb8aa3b, v21
	v_rcp_f32_e32 v64, v2
	v_add_f32_e32 v2, 1.0, v3
	v_add_f32_e32 v3, v46, v22
	v_exp_f32_e32 v24, v21
	v_mul_f32_e32 v3, 0xbfb8aa3b, v3
	v_exp_f32_e32 v3, v3
	v_add_f32_e32 v22, v30, v26
	v_mul_f32_e32 v22, 0xbfb8aa3b, v22
	v_rcp_f32_e32 v21, v2
	v_add_f32_e32 v2, 1.0, v24
	v_exp_f32_e32 v24, v22
	v_rcp_f32_e32 v65, v2
	v_add_f32_e32 v2, 1.0, v3
	v_add_f32_e32 v3, v47, v23
	v_mul_f32_e32 v3, 0xbfb8aa3b, v3
	v_add_f32_e32 v23, v31, v27
	v_exp_f32_e32 v3, v3
	v_mul_f32_e32 v23, 0xbfb8aa3b, v23
	v_rcp_f32_e32 v22, v2
	v_add_f32_e32 v2, 1.0, v24
	v_exp_f32_e32 v24, v23
	v_rcp_f32_e32 v66, v2
	v_add_f32_e32 v2, 1.0, v3
	v_add_f32_e32 v3, v48, v36
	v_rcp_f32_e32 v23, v2
	v_add_f32_e32 v2, 1.0, v24
	v_mul_f32_e32 v3, 0xbfb8aa3b, v3
	s_waitcnt lgkmcnt(0)
	v_add_f32_e32 v24, v32, v40
	v_exp_f32_e32 v3, v3
	v_mul_f32_e32 v24, 0xbfb8aa3b, v24
	v_exp_f32_e32 v25, v24
	v_rcp_f32_e32 v67, v2
	v_add_f32_e32 v2, 1.0, v3
	v_add_f32_e32 v3, v49, v37
	v_rcp_f32_e32 v24, v2
	v_add_f32_e32 v2, 1.0, v25
	v_mul_f32_e32 v3, 0xbfb8aa3b, v3
	v_add_f32_e32 v25, v33, v41
	v_exp_f32_e32 v3, v3
	v_mul_f32_e32 v25, 0xbfb8aa3b, v25
	v_exp_f32_e32 v26, v25
	v_add_f32_e32 v27, v34, v42
	v_add_f32_e32 v3, 1.0, v3
	v_mul_f32_e32 v27, 0xbfb8aa3b, v27
	v_add_f32_e32 v29, v35, v43
	v_rcp_f32_e32 v25, v3
	v_add_f32_e32 v3, 1.0, v26
	v_add_f32_e32 v26, v50, v38
	v_exp_f32_e32 v27, v27
	v_mul_f32_e32 v28, 0xbfb8aa3b, v28
	v_mul_f32_e32 v29, 0xbfb8aa3b, v29
	v_mul_f32_e32 v26, 0xbfb8aa3b, v26
	v_exp_f32_e32 v28, v28
	v_exp_f32_e32 v29, v29
	v_exp_f32_e32 v26, v26
	v_add_f32_e32 v27, 1.0, v27
	v_pk_mul_f32 v[44:45], v[74:75], s[86:87] op_sel_hi:[1,0]
	v_pk_mul_f32 v[46:47], v[84:85], s[86:87] op_sel_hi:[1,0]
	v_rcp_f32_e32 v72, v27
	v_add_f32_e32 v27, 1.0, v28
	v_add_f32_e32 v73, 1.0, v29
	v_cvt_pk_bf16_f32 v28, v44, 0
	v_cvt_pk_bf16_f32 v29, v45, 0
	v_cvt_pk_bf16_f32 v32, v46, 0
	v_cvt_pk_bf16_f32 v33, v47, 0
	v_add_f32_e32 v26, 1.0, v26
	v_lshlrev_b32_e32 v29, 16, v29
	v_lshlrev_b32_e32 v28, 16, v28
	v_lshlrev_b32_e32 v33, 16, v33
	v_lshlrev_b32_e32 v32, 16, v32
	v_rcp_f32_e32 v26, v26
	v_rcp_f32_e32 v27, v27
	v_pk_fma_f32 v[30:31], v[74:75], s[86:87], v[28:29] op_sel_hi:[1,0,1] neg_lo:[0,0,1] neg_hi:[0,0,1]
	v_pk_fma_f32 v[34:35], v[84:85], s[86:87], v[32:33] op_sel_hi:[1,0,1] neg_lo:[0,0,1] neg_hi:[0,0,1]
	v_pk_mul_f32 v[74:75], v[60:61], s[86:87] op_sel_hi:[1,0]
	v_pk_mul_f32 v[84:85], v[62:63], s[86:87] op_sel_hi:[1,0]
	v_cvt_pk_bf16_f32 v36, v74, 0
	v_cvt_pk_bf16_f32 v37, v75, 0
	v_cvt_pk_bf16_f32 v40, v84, 0
	v_cvt_pk_bf16_f32 v41, v85, 0
	v_lshlrev_b32_e32 v37, 16, v37
	v_lshlrev_b32_e32 v36, 16, v36
	v_lshlrev_b32_e32 v41, 16, v41
	v_lshlrev_b32_e32 v40, 16, v40
	v_pk_mul_f32 v[68:69], v[24:25], s[86:87] op_sel_hi:[1,0]
	v_pk_fma_f32 v[38:39], v[60:61], s[86:87], v[36:37] op_sel_hi:[1,0,1] neg_lo:[0,0,1] neg_hi:[0,0,1]
	v_pk_fma_f32 v[42:43], v[62:63], s[86:87], v[40:41] op_sel_hi:[1,0,1] neg_lo:[0,0,1] neg_hi:[0,0,1]
	v_pk_mul_f32 v[60:61], v[20:21], s[86:87] op_sel_hi:[1,0]
	v_pk_mul_f32 v[62:63], v[22:23], s[86:87] op_sel_hi:[1,0]
	v_cvt_pk_bf16_f32 v70, v68, 0
	v_cvt_pk_bf16_f32 v71, v69, 0
	v_cvt_pk_bf16_f32 v48, v60, 0
	v_cvt_pk_bf16_f32 v49, v61, 0
	v_cvt_pk_bf16_f32 v50, v62, 0
	v_cvt_pk_bf16_f32 v51, v63, 0
	v_lshlrev_b32_e32 v87, 16, v71
	v_lshlrev_b32_e32 v86, 16, v70
	v_pk_mul_f32 v[70:71], v[26:27], s[86:87] op_sel_hi:[1,0]
	v_lshlrev_b32_e32 v49, 16, v49
	v_lshlrev_b32_e32 v48, 16, v48
	v_lshlrev_b32_e32 v51, 16, v51
	v_lshlrev_b32_e32 v50, 16, v50
	v_cvt_pk_bf16_f32 v88, v70, 0
	v_cvt_pk_bf16_f32 v89, v71, 0
	v_pk_fma_f32 v[20:21], v[20:21], s[86:87], v[48:49] op_sel_hi:[1,0,1] neg_lo:[0,0,1] neg_hi:[0,0,1]
	v_pk_fma_f32 v[22:23], v[22:23], s[86:87], v[50:51] op_sel_hi:[1,0,1] neg_lo:[0,0,1] neg_hi:[0,0,1]
	v_pk_fma_f32 v[24:25], v[24:25], s[86:87], v[86:87] op_sel_hi:[1,0,1] neg_lo:[0,0,1] neg_hi:[0,0,1]
	v_lshlrev_b32_e32 v89, 16, v89
	v_lshlrev_b32_e32 v88, 16, v88
	v_cvt_pk_bf16_f32 v28, v28, v29
	v_cvt_pk_bf16_f32 v29, v32, v33
	v_cvt_pk_bf16_f32 v32, v36, v37
	v_cvt_pk_bf16_f32 v33, v40, v41
	v_add_u32_e32 v36, 0x9000, v1
	ds_write2_b64 v36, v[28:29], v[32:33] offset1:2
	v_cvt_pk_bf16_f32 v28, v48, v49
	v_cvt_pk_bf16_f32 v29, v50, v51
	v_cvt_pk_bf16_f32 v32, v86, v87
	v_cvt_pk_bf16_f32 v33, v88, v89
	v_cvt_pk_bf16_f32 v20, v20, v21
	v_cvt_pk_bf16_f32 v21, v22, v23
	v_cvt_pk_bf16_f32 v22, v24, v25
	v_pk_fma_f32 v[24:25], v[26:27], s[86:87], v[88:89] op_sel_hi:[1,0,1] neg_lo:[0,0,1] neg_hi:[0,0,1]
	ds_write2_b64 v36, v[28:29], v[32:33] offset0:4 offset1:6
	v_cvt_pk_bf16_f32 v28, v30, v31
	v_cvt_pk_bf16_f32 v29, v34, v35
	v_cvt_pk_bf16_f32 v30, v38, v39
	v_cvt_pk_bf16_f32 v31, v42, v43
	v_add_u32_e32 v1, 0xb000, v1
	v_cvt_pk_bf16_f32 v23, v24, v25
	ds_write2_b64 v1, v[28:29], v[30:31] offset0:128 offset1:130
	ds_write2_b64 v1, v[20:21], v[22:23] offset0:132 offset1:134
	v_mov_b32_e32 v1, v180
	s_waitcnt lgkmcnt(0)
	s_barrier
	v_rcp_f32_e32 v59, v59
	v_add_u32_e32 v20, s42, v1
	v_ashrrev_i32_e32 v20, 3, v20
	v_cmp_gt_i32_e32 vcc, 32, v20
	v_lshlrev_b32_e32 v20, 8, v20
	v_lshlrev_b32_e32 v1, 5, v1
	v_cndmask_b32_e32 v21, v98, v99, vcc
	v_and_b32_e32 v20, 0x1f00, v20
	v_and_b32_e32 v1, 0xe0, v1
	v_add3_u32 v1, v21, v20, v1
	ds_write_b128 v1, v[76:79]
	ds_write_b128 v1, v[80:83] offset:16
	v_mov_b32_e32 v1, v180
	v_rcp_f32_e32 v2, v2
	v_ashrrev_i32_e32 v24, 2, v1
	v_lshlrev_b32_e32 v22, 2, v1
	v_and_b32_e32 v20, 16, v1
	v_and_b32_e32 v148, -8, v24
	v_lshrrev_b32_e32 v21, 2, v1
	v_and_b32_e32 v22, 12, v22
	v_and_or_b32 v21, v21, 3, v148
	v_or3_b32 v20, v20, v22, s91
	v_lshlrev_b32_e32 v20, 1, v20
	v_mul_lo_u32 v21, v21, s64
	v_add3_u32 v25, s76, v20, v21
	ds_read_b64_tr_b16 v[20:21], v25 offset:36864
	ds_read_b64_tr_b16 v[22:23], v25 offset:37440
	ds_read_b64_tr_b16 v[36:37], v25 offset:39168
	ds_read_b64_tr_b16 v[38:39], v25 offset:39744
	ds_read_b64_tr_b16 v[40:41], v25 offset:41472
	ds_read_b64_tr_b16 v[42:43], v25 offset:42048
	ds_read_b64_tr_b16 v[48:49], v25 offset:43776
	ds_read_b64_tr_b16 v[50:51], v25 offset:44352
	ds_read_b64_tr_b16 v[76:77], v25 offset:46080
	ds_read_b64_tr_b16 v[78:79], v25 offset:46656
	ds_read_b64_tr_b16 v[80:81], v25 offset:48384
	ds_read_b64_tr_b16 v[82:83], v25 offset:48960
	ds_read_b64_tr_b16 v[86:87], v25 offset:50688
	ds_read_b64_tr_b16 v[88:89], v25 offset:51264
	ds_read_b64_tr_b16 v[90:91], v25 offset:52992
	ds_read_b64_tr_b16 v[92:93], v25 offset:53568
	v_and_or_b32 v1, v1, 31, s43
	v_rcp_f32_e32 v3, v3
	v_rcp_f32_e32 v73, v73
	v_cmp_gt_i32_e32 vcc, v148, v1
	v_or_b32_e32 v24, 7, v24
	s_waitcnt lgkmcnt(0)
	s_barrier
	s_bitcmp1_b32 s60, 0
	s_cbranch_scc1 .Lstg_1
	s_sleep 16
